# v16 plus retention unit prologue: decay-constant exp/log chain runs after the Q loads and first K tile DMA are issued
# speedup vs baseline: 1.0025x; 1.0025x over previous
; #define RET_UNI(x) x = __uint_as_float(__builtin_amdgcn_readfirstlane(__float_as_uint(x)))
; __device__ __forceinline__ void retention_unit(LAS unsigned char* lds, const Args& a, int b, int hh, int qb, int wid, int lane) {
;     ...
;     c.lf2 = -log1pf(expf(-a.dec_f[hh])) * 1.4426950408889634f; c.lb2 = -log1pf(expf(-a.dec_b[hh])) * 1.4426950408889634f;
;     c.iabs = qb * 128 + rg * 32 + r; c.qr0 = qb * 128 + rg * 32; c.r = r; c.h = h; c.hf = hf;
;     c.gi = exp2f(-c.lf2); { const float t2 = c.gi * c.gi, t4 = t2 * t2; c.gi8 = t4 * t4; } c.gb = exp2f(c.lb2); { const float t2 = c.gb * c.gb, t4 = t2 * t2; c.gb8 = t4 * t4; }
;     ...
;     RET_UNI(c.lf2); RET_UNI(c.lb2); RET_UNI(c.gi); RET_UNI(c.gi8); RET_UNI(c.gb); RET_UNI(c.gb8);
;     ...
;     bf16x8 qf[16];
;     { const bf16_t* qp = Qp + (size_t)(b * SEQ + c.iabs) * DM + hh * 256 + 8 * h;
; #pragma unroll
;       for (int s = 0; s < 16; ++s) qf[s] = *(const bf16x8*)(qp + 16 * s); }
;     f32x16 O[4];
; #pragma unroll
;     for (int d = 0; d < 4; ++d)
; #pragma unroll
;         for (int i = 0; i < 16; ++i) O[d][i] = 0.f;
;     c.Kl0 = Kp + (size_t)(b * SEQ) * DM + hh * 256; c.Vl0 = Vp + (size_t)(b * SEQ) * DM + hh * 256;
;     const int tq = (lane & 15) >> 2, tp = lane & 3, g16 = (lane >> 4) & 1;
;     c.tq = tq; c.vlane = (4 * h + tq) * 512 + (2 * g16 + (tp >> 1)) * 16 + (tp & 1) * 8 + hf * 256;
;     c.myx = ((wid * 2) * 64 + lane) * 16; c.pbx = (((wid & ~1) * 2) * 64 + lane) * 16;
;     ret_issue<false>(lds, c.Kl0 + (size_t)(kbeg * 64) * DM, wid, lane);
.LBB0_659:
	s_ashr_i32 s0, s75, 31
	s_lshr_b32 s0, s0, 30
	s_add_i32 s0, s75, s0
	s_ashr_i32 s41, s40, 31
	s_ashr_i32 s0, s0, 2
	s_lshl_b64 s[42:43], s[40:41], 2
	s_add_u32 s22, s36, s42
	v_mov_b32_e32 v30, v177
	s_addc_u32 s23, s37, s43
	global_load_dword v210, v145, s[22:23]
	s_add_u32 s22, s38, s42
	s_addc_u32 s23, s39, s43
	global_load_dword v212, v145, s[22:23]
	v_and_b32_e32 v208, 31, v30
	v_ashrrev_i32_e32 v184, 5, v30
	v_lshlrev_b32_e32 v146, 3, v184
	v_ashrrev_i32_e32 v147, 31, v146
	s_mov_b64 s[14:15], s[90:91]
	v_lshlrev_b32_e32 v209, 2, v184
	v_bitop3_b32 v35, v209, v208, 12 bitop3:0x6c
	s_lshl_b32 s9, s75, 7
	s_add_i32 s41, s9, s60
	v_or_b32_e32 v185, s41, v208
	s_lshl_b32 s42, s11, 11
	s_nop 0
	s_lshl_b32 s46, s40, 8
	s_nop 0
	s_nop 0
	s_nop 0
	v_add_u32_e32 v0, s42, v185
	s_nop 0
	v_ashrrev_i32_e32 v1, 31, v0
	v_lshlrev_b64 v[0:1], 12, v[0:1]
	s_ashr_i32 s47, s46, 31
	v_lshl_add_u64 v[0:1], s[12:13], 0, v[0:1]
	s_lshl_b64 s[22:23], s[46:47], 1
	v_lshl_add_u64 v[0:1], v[0:1], 0, s[22:23]
	v_lshl_add_u64 v[0:1], v[146:147], 1, v[0:1]
	global_load_dwordx4 v[140:143], v[0:1], off
	global_load_dwordx4 v[136:139], v[0:1], off offset:32
	global_load_dwordx4 v[132:135], v[0:1], off offset:64
	global_load_dwordx4 v[128:131], v[0:1], off offset:96
	global_load_dwordx4 v[124:127], v[0:1], off offset:128
	global_load_dwordx4 v[120:123], v[0:1], off offset:160
	global_load_dwordx4 v[116:119], v[0:1], off offset:192
	global_load_dwordx4 v[112:115], v[0:1], off offset:224
	global_load_dwordx4 v[108:111], v[0:1], off offset:256
	global_load_dwordx4 v[104:107], v[0:1], off offset:288
	global_load_dwordx4 v[100:103], v[0:1], off offset:320
	global_load_dwordx4 v[96:99], v[0:1], off offset:352
	global_load_dwordx4 v[92:95], v[0:1], off offset:384
	global_load_dwordx4 v[88:91], v[0:1], off offset:416
	global_load_dwordx4 v[84:87], v[0:1], off offset:448
	global_load_dwordx4 v[80:83], v[0:1], off offset:480
	s_ashr_i32 s43, s42, 31
	s_lshl_b64 s[48:49], s[42:43], 12
	s_add_u32 s3, s16, s48
	s_addc_u32 s50, s17, s49
	s_add_u32 s43, s3, s22
	s_addc_u32 s88, s50, s23
	s_add_u32 s3, s18, s48
	s_addc_u32 s48, s19, s49
	s_add_u32 s90, s3, s22
	s_nop 0
	s_addc_u32 s91, s48, s23
	s_lshl_b32 s48, s0, 9
	s_nop 0
	s_nop 0
	s_ashr_i32 s49, s48, 31
	s_nop 0
	s_nop 0
	s_lshl_b64 s[22:23], s[48:49], 12
	v_add_u32_e32 v0, s63, v184
	s_nop 0
	s_add_u32 s50, s43, s22
	v_ashrrev_i32_e32 v1, 31, v0
	s_addc_u32 s51, s88, s23
	v_bitop3_b32 v31, v0, v208, 15 bitop3:0x6c
	v_lshlrev_b64 v[148:149], 12, v[0:1]
	v_lshl_add_u64 v[0:1], s[50:51], 0, v[148:149]
	v_lshlrev_b32_e32 v144, 4, v31
	v_lshl_add_u64 v[0:1], v[0:1], 0, v[144:145]
	s_add_i32 s3, s64, 0
	s_mov_b32 s49, m0
	s_mov_b32 m0, s3
	s_nop 0
	global_load_lds_dwordx4 v[0:1], off
	s_mov_b32 m0, s49
	v_add_u32_e32 v0, s65, v184
	v_ashrrev_i32_e32 v1, 31, v0
	v_bitop3_b32 v32, v0, v208, 15 bitop3:0x6c
	v_lshlrev_b64 v[150:151], 12, v[0:1]
	v_lshl_add_u64 v[2:3], s[50:51], 0, v[150:151]
	v_lshlrev_b32_e32 v4, 4, v32
	v_mov_b32_e32 v5, v145
	v_lshl_add_u64 v[2:3], v[2:3], 0, v[4:5]
	s_add_i32 s3, s66, 0
	s_mov_b32 s49, m0
	s_mov_b32 m0, s3
	s_nop 0
	global_load_lds_dwordx4 v[2:3], off
	s_mov_b32 m0, s49
	v_add_u32_e32 v2, s67, v184
	v_ashrrev_i32_e32 v3, 31, v2
	v_bitop3_b32 v33, v2, v208, 15 bitop3:0x6c
	v_lshlrev_b64 v[152:153], 12, v[2:3]
	v_lshl_add_u64 v[2:3], s[50:51], 0, v[152:153]
	v_lshlrev_b32_e32 v6, 4, v33
	v_mov_b32_e32 v7, v145
	v_lshl_add_u64 v[2:3], v[2:3], 0, v[6:7]
	s_add_i32 s3, s68, 0
	s_mov_b32 s49, m0
	s_mov_b32 m0, s3
	s_nop 0
	global_load_lds_dwordx4 v[2:3], off
	s_mov_b32 m0, s49
	v_add_u32_e32 v2, s69, v184
	v_ashrrev_i32_e32 v3, 31, v2
	v_lshlrev_b64 v[154:155], 12, v[2:3]
	v_lshl_add_u64 v[8:9], s[50:51], 0, v[154:155]
	s_or_b32 s50, s48, 64
	s_ashr_i32 s51, s50, 31
	v_bitop3_b32 v34, v2, v208, 15 bitop3:0x6c
	s_add_i32 s3, s70, 0
	s_lshl_b64 s[50:51], s[50:51], 12
	v_lshlrev_b32_e32 v10, 4, v34
	v_mov_b32_e32 v11, v145
	s_add_u32 s50, s43, s50
	v_lshl_add_u64 v[8:9], v[8:9], 0, v[10:11]
	s_addc_u32 s51, s88, s51
	s_mov_b32 s49, m0
	s_mov_b32 m0, s3
	s_nop 0
	global_load_lds_dwordx4 v[8:9], off
	s_mov_b32 m0, s49
	v_lshl_add_u64 v[8:9], s[50:51], 0, v[148:149]
	s_mov_b32 s1, 0xbfb8aa3b
	s_mov_b32 s3, 0xc2b17218
	s_mov_b32 s98, 0x3f317218
	s_mov_b32 s100, 0x33800000
	s_nop 0
	s_nop 0
	s_waitcnt vmcnt(21)
	v_mul_f32_e32 v211, 0xbfb8aa3b, v210
	v_fma_f32 v213, v210, s1, -v211
	v_rndne_f32_e32 v214, v211
	v_fmac_f32_e32 v213, 0xb2a5705f, v210
	v_sub_f32_e32 v211, v211, v214
	s_waitcnt vmcnt(20)
; __device__ __forceinline__ void retention_unit(LAS unsigned char* lds, const Args& a, int b, int hh, int qb, int wid, int lane) {
;     ...
;     c.lf2 = -log1pf(expf(-a.dec_f[hh])) * 1.4426950408889634f; c.lb2 = -log1pf(expf(-a.dec_b[hh])) * 1.4426950408889634f;
;     c.iabs = qb * 128 + rg * 32 + r; c.qr0 = qb * 128 + rg * 32; c.r = r; c.h = h; c.hf = hf;
;     c.gi = exp2f(-c.lf2); { const float t2 = c.gi * c.gi, t4 = t2 * t2; c.gi8 = t4 * t4; } c.gb = exp2f(c.lb2); { const float t2 = c.gb * c.gb, t4 = t2 * t2; c.gb8 = t4 * t4; }
	v_mul_f32_e32 v215, 0xbfb8aa3b, v212
	v_add_f32_e32 v211, v211, v213
	v_cvt_i32_f32_e32 v214, v214
	v_fma_f32 v213, v212, s1, -v215
	v_rndne_f32_e32 v216, v215
	v_exp_f32_e32 v211, v211
	v_fmac_f32_e32 v213, 0xb2a5705f, v212
	v_sub_f32_e32 v215, v215, v216
	v_add_f32_e32 v213, v215, v213
	v_cvt_i32_f32_e32 v216, v216
	v_exp_f32_e32 v213, v213
	s_mov_b32 s1, 0x42ce8ed0
	v_ldexp_f32 v211, v211, v214
	v_cmp_nlt_f32_e32 vcc, s1, v210
	s_nop 1
	v_cndmask_b32_e32 v211, 0, v211, vcc
	v_cmp_ngt_f32_e32 vcc, s3, v210
	v_ldexp_f32 v210, v213, v216
	s_nop 0
	v_cndmask_b32_e32 v214, v206, v211, vcc
	v_add_f32_e32 v213, 1.0, v214
	v_cmp_nlt_f32_e32 vcc, s1, v212
	v_add_f32_e32 v216, -1.0, v213
	v_frexp_mant_f32_e32 v217, v213
	v_cndmask_b32_e32 v215, 0, v210, vcc
	v_cvt_f64_f32_e32 v[210:211], v213
	v_cmp_ngt_f32_e32 vcc, s3, v212
	s_mov_b32 s3, 0x3f2aaaab
	v_frexp_exp_i32_f64_e32 v210, v[210:211]
	v_cndmask_b32_e32 v212, v206, v215, vcc
	v_sub_f32_e32 v215, v216, v213
	v_cmp_gt_f32_e32 vcc, s3, v217
	v_sub_f32_e32 v216, v214, v216
	v_add_f32_e32 v218, 1.0, v212
	v_add_f32_e32 v215, 1.0, v215
	v_subbrev_co_u32_e32 v217, vcc, 0, v210, vcc
	v_add_f32_e32 v219, -1.0, v218
	v_add_f32_e32 v215, v216, v215
	v_sub_u32_e32 v216, 0, v217
	v_cvt_f32_i32_e32 v217, v217
	v_sub_f32_e32 v220, v219, v218
	v_ldexp_f32 v213, v213, v216
	v_sub_f32_e32 v219, v212, v219
	v_ldexp_f32 v215, v215, v216
	v_add_f32_e32 v216, 1.0, v220
	v_add_f32_e32 v220, -1.0, v213
	v_add_f32_e32 v221, 1.0, v213
	v_add_f32_e32 v216, v219, v216
	v_add_f32_e32 v219, 1.0, v220
	v_add_f32_e32 v222, -1.0, v221
	v_sub_f32_e32 v219, v213, v219
	v_sub_f32_e32 v213, v213, v222
	v_mul_f32_e32 v222, 0x3f317218, v217
	v_add_f32_e32 v219, v215, v219
	v_add_f32_e32 v213, v215, v213
	v_fma_f32 v215, v217, s98, -v222
	v_add_f32_e32 v223, v220, v219
	v_add_f32_e32 v224, v221, v213
	v_fmac_f32_e32 v215, 0xb102e308, v217
	v_sub_f32_e32 v217, v220, v223
	v_sub_f32_e32 v220, v221, v224
	v_rcp_f32_e32 v221, v224
	v_add_f32_e32 v225, v222, v215
	v_add_f32_e32 v217, v219, v217
	v_sub_f32_e32 v219, v225, v222
	v_sub_f32_e32 v215, v215, v219
	v_mul_f32_e32 v219, v223, v221
	v_add_f32_e32 v213, v213, v220
	v_mul_f32_e32 v220, v224, v219
	v_fma_f32 v222, v219, v224, -v220
	v_fmac_f32_e32 v222, v219, v213
	v_add_f32_e32 v226, v220, v222
	v_sub_f32_e32 v227, v223, v226
	v_sub_f32_e32 v220, v226, v220
	v_sub_f32_e32 v223, v223, v227
	v_sub_f32_e32 v220, v220, v222
	v_sub_f32_e32 v222, v223, v226
	v_add_f32_e32 v217, v217, v222
	v_add_f32_e32 v217, v220, v217
	v_add_f32_e32 v220, v227, v217
	v_mul_f32_e32 v222, v221, v220
	v_sub_f32_e32 v223, v227, v220
	v_mul_f32_e32 v226, v224, v222
	v_add_f32_e32 v217, v217, v223
	v_add_f32_e32 v223, v219, v222
	v_fma_f32 v224, v222, v224, -v226
	v_sub_f32_e32 v219, v223, v219
	v_fmac_f32_e32 v224, v222, v213
	v_sub_f32_e32 v213, v222, v219
	v_add_f32_e32 v219, v226, v224
	v_sub_f32_e32 v222, v219, v226
	v_sub_f32_e32 v226, v220, v219
	v_sub_f32_e32 v220, v220, v226
	v_sub_f32_e32 v219, v220, v219
	v_sub_f32_e32 v222, v222, v224
	v_add_f32_e32 v217, v217, v219
	v_add_f32_e32 v217, v222, v217
	v_add_f32_e32 v217, v226, v217
	v_mul_f32_e32 v217, v221, v217
	v_add_f32_e32 v213, v213, v217
	v_add_f32_e32 v217, v223, v213
	v_mul_f32_e32 v219, v217, v217
	v_fmamk_f32 v222, v219, 0x3e9b6dac, v203
	v_sub_f32_e32 v220, v217, v223
	v_ldexp_f32 v221, v217, 1
	v_mul_f32_e32 v217, v217, v219
	v_fmaak_f32 v219, v219, v222, 0x3f2aaada
	v_mul_f32_e32 v217, v217, v219
	v_add_f32_e32 v219, v221, v217
	v_sub_f32_e32 v213, v213, v220
	v_sub_f32_e32 v220, v219, v221
	v_ldexp_f32 v213, v213, 1
	v_sub_f32_e32 v217, v217, v220
	v_add_f32_e32 v213, v213, v217
	v_add_f32_e32 v217, v219, v213
	v_sub_f32_e32 v219, v217, v219
	v_add_f32_e32 v220, v225, v217
	v_sub_f32_e32 v213, v213, v219
	v_sub_f32_e32 v219, v220, v225
	v_sub_f32_e32 v221, v220, v219
	v_sub_f32_e32 v217, v217, v219
	v_add_f32_e32 v219, v215, v213
	v_sub_f32_e32 v221, v225, v221
	v_sub_f32_e32 v222, v219, v215
	v_add_f32_e32 v217, v217, v221
	v_sub_f32_e32 v221, v219, v222
	v_sub_f32_e32 v213, v213, v222
	v_sub_f32_e32 v215, v215, v221
	v_add_f32_e32 v217, v219, v217
	v_add_f32_e32 v213, v213, v215
	v_add_f32_e32 v215, v220, v217
	v_sub_f32_e32 v219, v215, v220
	v_sub_f32_e32 v217, v217, v219
	v_add_f32_e32 v213, v213, v217
	s_mov_b32 s1, 0x7f800000
	v_add_f32_e32 v213, v215, v213
	v_cmp_neq_f32_e32 vcc, s1, v214
	v_frexp_mant_f32_e32 v228, v218
	v_cvt_f64_f32_e32 v[210:211], v218
	v_cndmask_b32_e32 v213, v206, v213, vcc
	v_cmp_lt_f32_e64 vcc, |v214|, s100
	v_frexp_exp_i32_f64_e32 v210, v[210:211]
	s_nop 0
	v_cndmask_b32_e32 v213, v213, v214, vcc
	v_cmp_gt_f32_e32 vcc, s3, v228
	v_mul_f32_e32 v214, 0xbfb8aa3b, v213
	s_nop 0
	v_subbrev_co_u32_e32 v210, vcc, 0, v210, vcc
	v_sub_u32_e32 v211, 0, v210
	v_ldexp_f32 v215, v218, v211
	v_ldexp_f32 v211, v216, v211
	v_add_f32_e32 v216, -1.0, v215
	v_add_f32_e32 v219, 1.0, v215
	v_add_f32_e32 v217, 1.0, v216
	v_add_f32_e32 v228, -1.0, v219
	v_sub_f32_e32 v217, v215, v217
	v_sub_f32_e32 v215, v215, v228
	v_add_f32_e32 v217, v211, v217
	v_add_f32_e32 v211, v211, v215
	v_add_f32_e32 v215, v219, v211
	v_rcp_f32_e32 v228, v215
	v_add_f32_e32 v218, v216, v217
	v_sub_f32_e32 v216, v216, v218
	v_add_f32_e32 v216, v217, v216
	v_sub_f32_e32 v217, v219, v215
	v_add_f32_e32 v211, v211, v217
	v_mul_f32_e32 v217, v218, v228
	v_mul_f32_e32 v219, v215, v217
	v_fma_f32 v220, v217, v215, -v219
	v_fmac_f32_e32 v220, v217, v211
	v_add_f32_e32 v221, v219, v220
	v_sub_f32_e32 v222, v218, v221
	v_sub_f32_e32 v218, v218, v222
	v_sub_f32_e32 v219, v221, v219
	v_sub_f32_e32 v218, v218, v221
	v_add_f32_e32 v216, v216, v218
; #define RET_UNI(x) x = __uint_as_float(__builtin_amdgcn_readfirstlane(__float_as_uint(x)))
; template <bool PV, bool CTX>
; __device__ __forceinline__ void ret_iter(LAS unsigned char* lds, const RetC& c, int kt, f32x16 (&O)[4], const bf16x8 (&qf)[16], int wid, int lane) {
;     ...
;     asm volatile("s_waitcnt vmcnt(0) lgkmcnt(0)" ::: "memory");
;     __builtin_amdgcn_s_barrier();
; __device__ __forceinline__ void retention_unit(LAS unsigned char* lds, const Args& a, int b, int hh, int qb, int wid, int lane) {
;     ...
;     c.lf2 = -log1pf(expf(-a.dec_f[hh])) * 1.4426950408889634f; c.lb2 = -log1pf(expf(-a.dec_b[hh])) * 1.4426950408889634f;
;     c.iabs = qb * 128 + rg * 32 + r; c.qr0 = qb * 128 + rg * 32; c.r = r; c.h = h; c.hf = hf;
;     c.gi = exp2f(-c.lf2); { const float t2 = c.gi * c.gi, t4 = t2 * t2; c.gi8 = t4 * t4; } c.gb = exp2f(c.lb2); { const float t2 = c.gb * c.gb, t4 = t2 * t2; c.gb8 = t4 * t4; }
;     ...
;     RET_UNI(c.lf2); RET_UNI(c.lb2); RET_UNI(c.gi); RET_UNI(c.gi8); RET_UNI(c.gb); RET_UNI(c.gb8);
	v_sub_f32_e32 v218, v219, v220
	v_add_f32_e32 v216, v218, v216
	v_add_f32_e32 v218, v222, v216
	v_mul_f32_e32 v219, v228, v218
	v_mul_f32_e32 v220, v215, v219
	v_fma_f32 v215, v219, v215, -v220
	v_fmac_f32_e32 v215, v219, v211
	v_sub_f32_e32 v211, v222, v218
	v_add_f32_e32 v211, v216, v211
	v_add_f32_e32 v216, v220, v215
	v_sub_f32_e32 v221, v218, v216
	v_sub_f32_e32 v218, v218, v221
	v_sub_f32_e32 v220, v216, v220
	v_sub_f32_e32 v216, v218, v216
	v_add_f32_e32 v211, v211, v216
	v_sub_f32_e32 v215, v220, v215
	v_cvt_f32_i32_e32 v210, v210
	v_add_f32_e32 v211, v215, v211
	v_add_f32_e32 v215, v217, v219
	v_add_f32_e32 v211, v221, v211
	v_sub_f32_e32 v216, v215, v217
	v_mul_f32_e32 v211, v228, v211
	v_sub_f32_e32 v216, v219, v216
	v_add_f32_e32 v211, v216, v211
	v_mul_f32_e32 v219, 0x3f317218, v210
	v_add_f32_e32 v216, v215, v211
	v_fma_f32 v228, v210, s98, -v219
	v_mul_f32_e32 v217, v216, v216
	v_fmac_f32_e32 v228, 0xb102e308, v210
	v_sub_f32_e32 v210, v216, v215
	v_fmamk_f32 v218, v217, 0x3e9b6dac, v203
	v_sub_f32_e32 v210, v211, v210
	v_add_f32_e32 v211, v219, v228
	v_fmaak_f32 v218, v217, v218, 0x3f2aaada
	v_sub_f32_e32 v215, v211, v219
	v_ldexp_f32 v219, v216, 1
	v_mul_f32_e32 v216, v216, v217
	v_mul_f32_e32 v216, v216, v218
	v_add_f32_e32 v217, v219, v216
	v_sub_f32_e32 v218, v217, v219
	v_ldexp_f32 v210, v210, 1
	v_sub_f32_e32 v216, v216, v218
	v_add_f32_e32 v210, v210, v216
	v_add_f32_e32 v216, v217, v210
	v_sub_f32_e32 v217, v216, v217
	v_sub_f32_e32 v210, v210, v217
	v_add_f32_e32 v217, v211, v216
	v_sub_f32_e32 v218, v217, v211
	v_sub_f32_e32 v219, v217, v218
	v_sub_f32_e32 v215, v228, v215
	v_sub_f32_e32 v211, v211, v219
	v_sub_f32_e32 v216, v216, v218
	v_add_f32_e32 v211, v216, v211
	v_add_f32_e32 v216, v215, v210
	v_sub_f32_e32 v218, v216, v215
	v_sub_f32_e32 v219, v216, v218
	v_sub_f32_e32 v215, v215, v219
	v_sub_f32_e32 v210, v210, v218
	v_add_f32_e32 v211, v216, v211
	v_add_f32_e32 v210, v210, v215
	v_add_f32_e32 v215, v217, v211
	v_sub_f32_e32 v216, v215, v217
	v_sub_f32_e32 v211, v211, v216
	v_add_f32_e32 v210, v210, v211
	v_add_f32_e32 v210, v215, v210
	v_cmp_neq_f32_e32 vcc, s1, v212
	s_mov_b32 s1, 0x42fc0000
	s_nop 0
	v_cndmask_b32_e32 v210, v206, v210, vcc
	v_cmp_lt_f32_e64 vcc, |v212|, s100
	s_nop 0
	s_nop 0
	v_cndmask_b32_e32 v210, v210, v212, vcc
	v_cmp_lt_f32_e32 vcc, s1, v214
	s_and_b64 s[100:101], vcc, exec
	s_cselect_b32 s1, 0xffffffc0, 0
	v_cndmask_b32_e32 v211, 0, v207, vcc
	v_fmac_f32_e32 v211, 0x3fb8aa3b, v213
	v_exp_f32_e32 v211, v211
	v_mul_f32_e32 v212, 0xbfb8aa3b, v210
	v_readfirstlane_b32 s83, v214
	v_readfirstlane_b32 s84, v212
	v_ldexp_f32 v211, v211, s1
	s_mov_b32 s1, 0xc2fc0000
	v_cmp_gt_f32_e32 vcc, s1, v212
	s_and_b64 s[100:101], vcc, exec
	s_cselect_b32 s1, 0xffffffc0, 0
	v_cndmask_b32_e32 v215, 0, v207, vcc
	v_fmac_f32_e32 v215, 0xbfb8aa3b, v210
	v_exp_f32_e32 v210, v215
	s_nop 0
	v_mul_f32_e32 v213, v211, v211
	s_nop 0
	v_ldexp_f32 v210, v210, s1
	v_mul_f32_e32 v215, v210, v210
	v_readfirstlane_b32 s85, v210
	s_nop 0
	v_readfirstlane_b32 s1, v211
	s_nop 0
	s_nop 0
	v_mul_f32_e32 v213, v213, v213
	s_nop 0
	s_nop 0
	v_mul_f32_e32 v215, v215, v215
	v_mul_f32_e32 v210, v213, v213
	s_nop 0
	v_mul_f32_e32 v211, v215, v215
	v_readfirstlane_b32 s86, v210
	s_nop 0
	s_nop 0
	v_readfirstlane_b32 s87, v211
	s_waitcnt vmcnt(0) lgkmcnt(0)
	s_barrier
; template <bool PV, bool CTX>
; __device__ __forceinline__ void ret_iter(LAS unsigned char* lds, const RetC& c, int kt, f32x16 (&O)[4], const bf16x8 (&qf)[16], int wid, int lane) {
;     ...
;     asm volatile("s_waitcnt vmcnt(0) lgkmcnt(0)" ::: "memory");
;     __builtin_amdgcn_s_barrier();
;     asm volatile("" ::: "memory");
;     if (kt + 1 < c.kend) { const int k1 = kt + 1; ret_issue<false>(lds + (k1 & 1) * 65536, c.Kl0 + (size_t)(k1 * 64) * DM, wid, lane); }
;     if (kt < c.kend) ret_issue<true>(lds + 32768 + (kt & 1) * 65536, c.Vl0 + (size_t)(kt * 64) * DM, wid, lane);
;     const LAS unsigned char* Kl = lds + (kt & 1) * 65536;
;     int krow = 32 * c.hf + c.r; asm volatile("" : "+v"(krow));
;     const LAS unsigned char* kb = Kl + krow * 512; const int cx = ((krow & 15) ^ c.h) << 4;
;     f32x16 st;
; #pragma unroll
;     for (int i = 0; i < 16; ++i) st[i] = 0.f;
;     bf16x8 kf[2][4];
;     ...
;     RET_KREAD(0); RET_SB;
;     RET_KREAD(1); RET_KMMA(0); RET_SB;
;     RET_KREAD(2); RET_KMMA(1); RET_SB;
;     RET_KREAD(3); RET_KMMA(2); RET_SB;
;     if (PV) {
;         const LAS unsigned char* Vl = lds + 32768 + ((kt + 1) & 1) * 65536;
;         int vb = c.vlane; asm volatile("" : "+v"(vb));
;         const LAS unsigned char* vbase = Vl + vb;
;         const LAS unsigned char* pbase = xch + c.pbx;
;         const int vo0 = ((0 ^ c.tq) & 3) << 6, vo1 = ((1 ^ c.tq) & 3) << 6, vo2 = ((2 ^ c.tq) & 3) << 6, vo3 = ((3 ^ c.tq) & 3) << 6;
;         s16x4 vlo[2][4], vhi[2][4]; bf16x8 pf[2];
;     ...
;         RET_VREAD(0); RET_KMMA(3); RET_SB;
;         RET_VREAD(1); RET_VMMA(0); RET_SB;
;         RET_VREAD(2); RET_VMMA(1); RET_SB;
;         RET_VREAD(3); RET_VMMA(2); RET_SB;
;         RET_VMMA(3); RET_SB;
;     ...
;     } else {
;         RET_KMMA(3); RET_SB;
;     }
;     ...
;     {
;         const int k0 = kt * 64 + 32 * c.hf;
;         if (!CTX) {
;             const int d0 = c.iabs - (k0 + 4 * c.h);
;             if (k0 != c.qr0) {
;                 const bool fwd = c.qr0 > k0;
;                 const float m = fwd ? c.gi : c.gb, m8 = fwd ? c.gi8 : c.gb8;
;                 float w[4]; w[0] = __builtin_amdgcn_exp2f((float)d0 * (fwd ? c.lf2 : -c.lb2)); w[1] = w[0] * m; w[2] = w[1] * m; w[3] = w[2] * m;
; #pragma unroll
;                 for (int q4 = 0; q4 < 4; ++q4) {
; #pragma unroll
;                     for (int e = 0; e < 4; ++e) { st[4 * q4 + e] *= w[e]; w[e] *= m8; } }
	v_lshl_add_u64 v[8:9], v[8:9], 0, v[144:145]
	s_add_i32 s3, 0, 0x10000
	s_add_i32 s49, s64, s3
	s_mov_b32 s52, m0
	s_mov_b32 m0, s49
	s_nop 0
	global_load_lds_dwordx4 v[8:9], off
	s_mov_b32 m0, s52
	v_lshl_add_u64 v[8:9], s[50:51], 0, v[150:151]
	v_lshl_add_u64 v[4:5], v[8:9], 0, v[4:5]
	s_add_i32 s49, s66, s3
	s_mov_b32 s52, m0
	s_mov_b32 m0, s49
	s_nop 0
	global_load_lds_dwordx4 v[4:5], off
	s_mov_b32 m0, s52
	v_lshl_add_u64 v[4:5], s[50:51], 0, v[152:153]
	v_lshl_add_u64 v[4:5], v[4:5], 0, v[6:7]
	s_add_i32 s49, s68, s3
	s_add_i32 s3, s70, s3
	s_mov_b32 s52, m0
	s_mov_b32 m0, s49
	s_nop 0
	global_load_lds_dwordx4 v[4:5], off
	s_mov_b32 m0, s52
	v_lshl_add_u64 v[4:5], s[50:51], 0, v[154:155]
	s_add_u32 s22, s90, s22
	v_lshl_add_u64 v[4:5], v[4:5], 0, v[10:11]
	s_addc_u32 s23, s91, s23
	s_mov_b32 s49, m0
	s_mov_b32 m0, s3
	s_nop 0
	global_load_lds_dwordx4 v[4:5], off
	s_mov_b32 m0, s49
	v_lshl_add_u64 v[4:5], s[22:23], 0, v[148:149]
	v_lshlrev_b32_e32 v144, 4, v35
	v_lshlrev_b32_e32 v0, 2, v0
	v_lshl_add_u64 v[4:5], v[4:5], 0, v[144:145]
	v_bitop3_b32 v36, v0, v208, 12 bitop3:0x6c
	s_add_i32 s3, s64, s92
	s_mov_b32 s49, m0
	s_mov_b32 m0, s3
	s_nop 0
	global_load_lds_dwordx4 v[4:5], off
	s_mov_b32 m0, s49
	v_lshl_add_u64 v[0:1], s[22:23], 0, v[150:151]
	v_lshlrev_b32_e32 v4, 4, v36
	v_mov_b32_e32 v5, v145
	v_lshl_add_u64 v[0:1], v[0:1], 0, v[4:5]
	s_add_i32 s3, s66, s92
	s_mov_b32 s49, m0
	s_mov_b32 m0, s3
	s_nop 0
	global_load_lds_dwordx4 v[0:1], off
	s_mov_b32 m0, s49
	v_lshl_add_u64 v[0:1], s[22:23], 0, v[152:153]
	v_lshl_add_u64 v[0:1], v[0:1], 0, v[144:145]
	s_add_i32 s3, s68, s92
	s_mov_b32 s49, m0
	s_mov_b32 m0, s3
	s_nop 0
	global_load_lds_dwordx4 v[0:1], off
	s_mov_b32 m0, s49
	v_lshlrev_b32_e32 v0, 2, v2
	v_bitop3_b32 v37, v0, v208, 12 bitop3:0x6c
	v_lshl_add_u64 v[0:1], s[22:23], 0, v[154:155]
	v_lshlrev_b32_e32 v144, 4, v37
	v_lshl_add_u64 v[0:1], v[0:1], 0, v[144:145]
	v_or_b32_e32 v147, s71, v208
	s_add_i32 s3, s70, s92
	s_mov_b32 s22, m0
	s_mov_b32 m0, s3
	s_nop 0
	global_load_lds_dwordx4 v[0:1], off
	s_mov_b32 m0, s22
	v_mov_b32_e32 v0, v147
	s_nop 0
	v_bitop3_b32 v1, v0, v184, 15 bitop3:0x6c
	v_lshl_add_u32 v28, v0, 9, 0
	v_lshlrev_b32_e32 v29, 4, v1
	v_add_u32_e32 v0, v28, v29
	v_xad_u32 v4, v29, 32, v28
	ds_read_b128 v[0:3], v0
	ds_read_b128 v[16:19], v4
	v_xad_u32 v4, v29, 64, v28
	v_xad_u32 v5, v29, s6, v28
	ds_read_b128 v[20:23], v4
	ds_read_b128 v[24:27], v5
	v_xad_u32 v4, v29, s79, v28
	v_xad_u32 v5, v29, s7, v28
	ds_read_b128 v[38:41], v4
	ds_read_b128 v[42:45], v5
	v_xad_u32 v4, v29, s34, v28
	v_xad_u32 v5, v29, s35, v28
	ds_read_b128 v[46:49], v4
	ds_read_b128 v[50:53], v5
	s_waitcnt vmcnt(15) lgkmcnt(7)
	v_mfma_f32_32x32x16_bf16 v[0:15], v[0:3], v[140:143], 0
	v_xad_u32 v54, v29, s55, v28
	v_xad_u32 v58, v29, s94, v28
	s_waitcnt vmcnt(14) lgkmcnt(6)
	v_mfma_f32_32x32x16_bf16 v[0:15], v[16:19], v[136:139], v[0:15]
	v_xad_u32 v16, v29, s54, v28
	s_waitcnt vmcnt(13) lgkmcnt(5)
	v_mfma_f32_32x32x16_bf16 v[0:15], v[20:23], v[132:135], v[0:15]
	ds_read_b128 v[16:19], v16
	ds_read_b128 v[20:23], v54
	v_xad_u32 v54, v29, s93, v28
	ds_read_b128 v[54:57], v54
	ds_read_b128 v[58:61], v58
	s_waitcnt vmcnt(12) lgkmcnt(8)
	v_mfma_f32_32x32x16_bf16 v[0:15], v[24:27], v[128:131], v[0:15]
	s_waitcnt vmcnt(11) lgkmcnt(7)
	v_mfma_f32_32x32x16_bf16 v[0:15], v[38:41], v[124:127], v[0:15]
	v_xad_u32 v24, v29, s89, v28
	s_waitcnt vmcnt(10) lgkmcnt(6)
	v_mfma_f32_32x32x16_bf16 v[0:15], v[42:45], v[120:123], v[0:15]
	s_waitcnt vmcnt(9) lgkmcnt(5)
	v_mfma_f32_32x32x16_bf16 v[0:15], v[46:49], v[116:119], v[0:15]
	s_waitcnt vmcnt(8) lgkmcnt(4)
	v_mfma_f32_32x32x16_bf16 v[0:15], v[50:53], v[112:115], v[0:15]
	s_waitcnt vmcnt(7) lgkmcnt(3)
	v_mfma_f32_32x32x16_bf16 v[0:15], v[16:19], v[108:111], v[0:15]
	v_xad_u32 v16, v29, s95, v28
	s_waitcnt vmcnt(6) lgkmcnt(2)
	v_mfma_f32_32x32x16_bf16 v[0:15], v[20:23], v[104:107], v[0:15]
	v_xad_u32 v20, v29, s96, v28
	ds_read_b128 v[16:19], v16
	ds_read_b128 v[20:23], v20
	v_xad_u32 v28, v29, s33, v28
	ds_read_b128 v[24:27], v24
	ds_read_b128 v[38:41], v28
	s_waitcnt vmcnt(5) lgkmcnt(5)
	v_mfma_f32_32x32x16_bf16 v[0:15], v[54:57], v[100:103], v[0:15]
	s_waitcnt vmcnt(4) lgkmcnt(4)
	v_mfma_f32_32x32x16_bf16 v[0:15], v[58:61], v[96:99], v[0:15]
	s_waitcnt vmcnt(3) lgkmcnt(3)
	v_mfma_f32_32x32x16_bf16 v[0:15], v[16:19], v[92:95], v[0:15]
	s_waitcnt vmcnt(2) lgkmcnt(2)
	v_mfma_f32_32x32x16_bf16 v[0:15], v[20:23], v[88:91], v[0:15]
	s_waitcnt vmcnt(1) lgkmcnt(1)
	v_mfma_f32_32x32x16_bf16 v[0:15], v[24:27], v[84:87], v[0:15]
	s_waitcnt vmcnt(0) lgkmcnt(0)
	v_mfma_f32_32x32x16_bf16 v[0:15], v[38:41], v[80:83], v[0:15]
	s_or_b32 s3, s48, s71
	v_add_u32_e32 v16, s3, v209
	v_sub_u32_e32 v38, v185, v16
	v_cvt_f32_i32_e32 v41, v38
	s_xor_b32 s49, s84, 0x80000000
	s_cmp_lg_u32 s3, s41
	s_mov_b64 s[50:51], -1
	s_cbranch_scc0 .LBB0_661
	s_cmp_gt_i32 s41, s3
	v_mov_b32_e32 v16, s85
	v_mov_b32_e32 v17, s1
	s_cselect_b64 vcc, -1, 0
	v_cndmask_b32_e32 v23, v16, v17, vcc
	v_mov_b32_e32 v16, s84
	v_mov_b32_e32 v17, s83
	v_cndmask_b32_e64 v16, -v16, v17, vcc
	v_mul_f32_e32 v16, v16, v41
	v_exp_f32_e32 v18, v16
	v_mov_b32_e32 v16, s87
	v_mov_b32_e32 v17, s86
	v_cndmask_b32_e32 v28, v16, v17, vcc
	v_mul_f32_e32 v19, v23, v18
	v_mul_f32_e32 v22, v23, v19
	v_mul_f32_e32 v23, v23, v22
	v_pk_mul_f32 v[24:25], v[28:29], v[18:19] op_sel_hi:[0,1]
	v_pk_mul_f32 v[26:27], v[28:29], v[22:23] op_sel_hi:[0,1]
	v_pk_mul_f32 v[42:43], v[28:29], v[24:25] op_sel_hi:[0,1]
	v_pk_mul_f32 v[44:45], v[28:29], v[26:27] op_sel_hi:[0,1]
	v_mul_f32_e32 v39, v28, v44
	v_mul_f32_e32 v40, v28, v45
	v_pk_mul_f32 v[28:29], v[28:29], v[42:43] op_sel_hi:[0,1]
	v_pk_mul_f32 v[16:17], v[18:19], v[0:1]
	v_pk_mul_f32 v[20:21], v[24:25], v[4:5]
	v_pk_mul_f32 v[18:19], v[22:23], v[2:3]
	v_pk_mul_f32 v[22:23], v[26:27], v[6:7]
	v_pk_mul_f32 v[24:25], v[42:43], v[8:9]
	v_pk_mul_f32 v[26:27], v[44:45], v[10:11]
	v_pk_mul_f32 v[28:29], v[28:29], v[12:13]
	v_mul_f32_e32 v39, v39, v14
	s_mov_b64 s[50:51], 0

; __global__ void __launch_bounds__(512, 2) fwd_megakernel(Args a) {
	.amdhsa_kernel _Z14fwd_megakernel4Args
		.amdhsa_group_segment_fixed_size 0
		.amdhsa_private_segment_fixed_size 0
		.amdhsa_kernarg_size 440
		.amdhsa_user_sgpr_count 2
		.amdhsa_user_sgpr_dispatch_ptr 0
		.amdhsa_user_sgpr_queue_ptr 0
		.amdhsa_user_sgpr_kernarg_segment_ptr 1
		.amdhsa_user_sgpr_dispatch_id 0
		.amdhsa_user_sgpr_kernarg_preload_length 0
		.amdhsa_user_sgpr_kernarg_preload_offset 0
		.amdhsa_user_sgpr_private_segment_size 0
		.amdhsa_uses_dynamic_stack 0
		.amdhsa_enable_private_segment 0
		.amdhsa_system_sgpr_workgroup_id_x 1
		.amdhsa_system_sgpr_workgroup_id_y 0
		.amdhsa_system_sgpr_workgroup_id_z 0
		.amdhsa_system_sgpr_workgroup_info 0
		.amdhsa_system_vgpr_workitem_id 2
		.amdhsa_next_free_vgpr 243
		.amdhsa_next_free_sgpr 102
		.amdhsa_accum_offset 244
		.amdhsa_reserve_vcc 1
		.amdhsa_float_round_mode_32 0
		.amdhsa_float_round_mode_16_64 0
		.amdhsa_float_denorm_mode_32 3
		.amdhsa_float_denorm_mode_16_64 3
		.amdhsa_dx10_clamp 1
		.amdhsa_ieee_mode 1
		.amdhsa_fp16_overflow 0
		.amdhsa_tg_split 0
		.amdhsa_exception_fp_ieee_invalid_op 0
		.amdhsa_exception_fp_denorm_src 0
		.amdhsa_exception_fp_ieee_div_zero 0
		.amdhsa_exception_fp_ieee_overflow 0
		.amdhsa_exception_fp_ieee_underflow 0
		.amdhsa_exception_fp_ieee_inexact 0
		.amdhsa_exception_int_div_zero 0
	.end_amdhsa_kernel

; __global__ void __launch_bounds__(512, 2) fwd_megakernel(Args a) {
amdhsa.kernels:
  - .agpr_count:     0
    .args:
      - .offset:         0
        .size:           184
        .value_kind:     by_value
      - .offset:         184
        .size:           4
        .value_kind:     hidden_block_count_x
      - .offset:         188
        .size:           4
        .value_kind:     hidden_block_count_y
      - .offset:         192
        .size:           4
        .value_kind:     hidden_block_count_z
      - .offset:         196
        .size:           2
        .value_kind:     hidden_group_size_x
      - .offset:         198
        .size:           2
        .value_kind:     hidden_group_size_y
      - .offset:         200
        .size:           2
        .value_kind:     hidden_group_size_z
      - .offset:         202
        .size:           2
        .value_kind:     hidden_remainder_x
      - .offset:         204
        .size:           2
        .value_kind:     hidden_remainder_y
      - .offset:         206
        .size:           2
        .value_kind:     hidden_remainder_z
      - .offset:         224
        .size:           8
        .value_kind:     hidden_global_offset_x
      - .offset:         232
        .size:           8
        .value_kind:     hidden_global_offset_y
      - .offset:         240
        .size:           8
        .value_kind:     hidden_global_offset_z
      - .offset:         248
        .size:           2
        .value_kind:     hidden_grid_dims
      - .offset:         272
        .size:           8
        .value_kind:     hidden_multigrid_sync_arg
      - .offset:         304
        .size:           4
        .value_kind:     hidden_dynamic_lds_size
    .group_segment_fixed_size: 0
    .kernarg_segment_align: 8
    .kernarg_segment_size: 440
    .language:       OpenCL C
    .language_version:
      - 2
      - 0
    .max_flat_workgroup_size: 512
    .name:           _Z14fwd_megakernel4Args
    .private_segment_fixed_size: 0
    .sgpr_count:     108
    .sgpr_spill_count: 50
    .symbol:         _Z14fwd_megakernel4Args.kd
    .uniform_work_group_size: 1
    .uses_dynamic_stack: false
    .vgpr_count:     243
    .vgpr_spill_count: 0
    .wavefront_size: 64
